# G1+A1: also hoist the 8 RS scale loads in EpiRope8 no-rope path (counted waits)
# speedup vs baseline: 1.0173x; 1.0000x over previous
; __device__ __forceinline__ u32x4 pack8(const f32x4& v0, const f32x4& v1) { u32x4 w; w.x = cvt_pk_bf16(v0[0], v0[1]); w.y = cvt_pk_bf16(v0[2], v0[3]); w.z = cvt_pk_bf16(v1[0], v1[1]); w.w = cvt_pk_bf16(v1[2], v1[3]); return w; }
;     __device__ __forceinline__ void operator()(const i32x4 (&acc)[2][2][4][2], const Unit& u, int wr, int wc, int fr, int fq) const {
;         const int row0 = u.pm * BM + wr * 64 + fr, sec = u.pn >> 4, h = u.pn & 15, cw = wc * 32 + 8 * fq;
;         const bool do_rope = (u.pm < 64) && (sec < 2);
;         const int axis = wc >> 1, f0 = (wc & 1) * 16 + 4 * fq;
;         f32x4 csv[2][2];
; #pragma unroll
;         for (int bj = 0; bj < 2; ++bj)
; #pragma unroll
;             for (int n = 0; n < 2; ++n) csv[bj][n] = *(const f32x4*)(CS + u.pn * BM + bj * HALF + cw + 4 * n);
;         bf16_t* base; size_t rstride, bjstride;
;         if (sec < 2) { base = (sec == 0 ? QH : KH) + (size_t)(h * 2) * 17408 * 128; rstride = 128; bjstride = (size_t)17408 * 128; }
;         else if (sec == 2) { base = VH + (size_t)h * 17408 * 256; rstride = 256; bjstride = 128; }
;         else { base = GT + h * 256; rstride = 4096; bjstride = 128; }
;         if (!do_rope) {
; #pragma unroll
;             for (int ai = 0; ai < 2; ++ai)
; #pragma unroll
;                 for (int m = 0; m < 4; ++m) { const int row = row0 + ai * HALF + m * 16; bf16_t* rowp = base + (size_t)row * rstride + cw; const float rsv = RS[row];
; #pragma unroll
;                     for (int bj = 0; bj < 2; ++bj) *(u32x4*)(rowp + bj * bjstride) = pack8(__builtin_convertvector(acc[ai][bj][m][0], f32x4) * (csv[bj][0] * rsv), __builtin_convertvector(acc[ai][bj][m][1], f32x4) * (csv[bj][1] * rsv)); }
.LBB0_289:
	s_lshl_b32 s12, s2, 8
	s_add_i32 s12, s12, s93
	s_cmp_lt_i32 s2, 64
	s_cselect_b64 s[2:3], -1, 0
	s_and_b64 s[34:35], s[2:3], s[34:35]
	s_lshl_b64 s[2:3], s[6:7], 1
	s_add_u32 s2, s72, s2
	v_or_b32_e32 v168, s12, v179
	s_addc_u32 s3, s73, s3
	v_lshl_add_u64 v[164:165], s[2:3], 0, v[154:155]
	v_ashrrev_i32_e32 v169, 31, v168
	v_mad_u64_u32 v[166:167], s[2:3], s70, v168, 0
	v_mul_lo_u32 v170, s70, v169
	v_mul_lo_u32 v171, s71, v168
	v_readlane_b32 s2, v243, 51
	v_add3_u32 v167, v167, v170, v171
	v_readlane_b32 s3, v243, 52
	v_lshl_add_u64 v[176:177], v[166:167], 1, v[164:165]
	v_cvt_f32_i32_e32 v185, v143
	v_lshl_add_u64 v[166:167], v[168:169], 2, s[2:3]
	global_load_dword v178, v[166:167], off
	global_load_dword v244, v[166:167], off offset:64
	global_load_dword v245, v[166:167], off offset:128
	global_load_dword v246, v[166:167], off offset:192
	global_load_dword v247, v[166:167], off offset:512
	global_load_dword v248, v[166:167], off offset:576
	global_load_dword v249, v[166:167], off offset:640
	global_load_dword v250, v[166:167], off offset:704
	v_cvt_f32_i32_e32 v184, v142
	v_cvt_f32_i32_e32 v187, v145
	v_cvt_f32_i32_e32 v186, v144
	v_cvt_f32_i32_e32 v181, v139
	v_cvt_f32_i32_e32 v180, v138
	v_cvt_f32_i32_e32 v183, v141
	v_cvt_f32_i32_e32 v182, v140
	v_cvt_f32_i32_e32 v143, v127
	v_cvt_f32_i32_e32 v142, v126
	v_cvt_f32_i32_e32 v145, v129
	v_cvt_f32_i32_e32 v144, v128
	v_cvt_f32_i32_e32 v139, v123
	v_cvt_f32_i32_e32 v138, v122
	v_cvt_f32_i32_e32 v141, v125
	v_cvt_f32_i32_e32 v140, v124
	v_cvt_f32_i32_e32 v135, v135
	v_cvt_f32_i32_e32 v134, v134
	v_cvt_f32_i32_e32 v137, v137
	v_cvt_f32_i32_e32 v136, v136
	v_cvt_f32_i32_e32 v131, v131
	v_cvt_f32_i32_e32 v130, v130
	v_cvt_f32_i32_e32 v133, v133
	v_cvt_f32_i32_e32 v132, v132
	v_cvt_f32_i32_e32 v125, v111
	v_cvt_f32_i32_e32 v124, v110
	v_cvt_f32_i32_e32 v129, v113
	v_cvt_f32_i32_e32 v128, v112
	v_cvt_f32_i32_e32 v123, v107
	v_cvt_f32_i32_e32 v122, v106
	v_cvt_f32_i32_e32 v127, v109
	v_cvt_f32_i32_e32 v126, v108
	v_cvt_f32_i32_e32 v119, v119
	v_cvt_f32_i32_e32 v118, v118
	v_cvt_f32_i32_e32 v121, v121
	v_cvt_f32_i32_e32 v120, v120
	v_cvt_f32_i32_e32 v115, v115
	v_cvt_f32_i32_e32 v114, v114
	v_cvt_f32_i32_e32 v117, v117
	v_cvt_f32_i32_e32 v116, v116
	v_cvt_f32_i32_e32 v109, v95
	v_cvt_f32_i32_e32 v108, v94
	v_cvt_f32_i32_e32 v113, v97
	v_cvt_f32_i32_e32 v112, v96
	v_cvt_f32_i32_e32 v107, v91
	v_cvt_f32_i32_e32 v106, v90
	v_cvt_f32_i32_e32 v111, v93
	v_cvt_f32_i32_e32 v110, v92
	v_cvt_f32_i32_e32 v103, v103
	v_cvt_f32_i32_e32 v102, v102
	v_cvt_f32_i32_e32 v105, v105
	v_cvt_f32_i32_e32 v104, v104
	v_cvt_f32_i32_e32 v99, v99
	v_cvt_f32_i32_e32 v98, v98
	v_cvt_f32_i32_e32 v101, v101
	v_cvt_f32_i32_e32 v100, v100
	v_cvt_f32_i32_e32 v93, v87
	v_cvt_f32_i32_e32 v92, v86
	v_cvt_f32_i32_e32 v97, v89
	v_cvt_f32_i32_e32 v96, v88
	v_cvt_f32_i32_e32 v91, v83
	v_cvt_f32_i32_e32 v90, v82
	v_cvt_f32_i32_e32 v95, v85
	v_cvt_f32_i32_e32 v94, v84
	v_cvt_f32_i32_e32 v85, v79
	v_cvt_f32_i32_e32 v84, v78
	v_cvt_f32_i32_e32 v89, v81
	v_cvt_f32_i32_e32 v88, v80
	v_cvt_f32_i32_e32 v83, v75
	v_cvt_f32_i32_e32 v82, v74
	v_cvt_f32_i32_e32 v87, v77
	v_cvt_f32_i32_e32 v86, v76
	v_cvt_f32_i32_e32 v77, v63
	v_cvt_f32_i32_e32 v76, v62
	v_cvt_f32_i32_e32 v81, v65
	v_cvt_f32_i32_e32 v80, v64
	v_cvt_f32_i32_e32 v75, v59
	v_cvt_f32_i32_e32 v74, v58
	v_cvt_f32_i32_e32 v79, v61
	v_cvt_f32_i32_e32 v78, v60
	v_cvt_f32_i32_e32 v71, v71
	v_cvt_f32_i32_e32 v70, v70
	v_cvt_f32_i32_e32 v73, v73
	v_cvt_f32_i32_e32 v72, v72
	v_cvt_f32_i32_e32 v67, v67
	v_cvt_f32_i32_e32 v66, v66
	v_cvt_f32_i32_e32 v69, v69
	v_cvt_f32_i32_e32 v68, v68
	v_cvt_f32_i32_e32 v61, v47
	v_cvt_f32_i32_e32 v60, v46
	v_cvt_f32_i32_e32 v65, v49
	v_cvt_f32_i32_e32 v64, v48
	v_cvt_f32_i32_e32 v59, v43
	v_cvt_f32_i32_e32 v58, v42
	v_cvt_f32_i32_e32 v63, v45
	v_cvt_f32_i32_e32 v62, v44
	v_cvt_f32_i32_e32 v49, v55
	v_cvt_f32_i32_e32 v48, v54
	v_cvt_f32_i32_e32 v55, v57
	v_cvt_f32_i32_e32 v54, v56
	v_cvt_f32_i32_e32 v47, v51
	v_cvt_f32_i32_e32 v46, v50
	v_cvt_f32_i32_e32 v51, v53
	v_cvt_f32_i32_e32 v50, v52
	v_or_b32_e32 v174, 16, v168
	v_or_b32_e32 v172, 32, v168
	v_or_b32_e32 v170, 48, v168
	v_add_u32_e32 v205, 0x80, v168
	s_mov_b64 s[2:3], -1
	s_and_b64 vcc, exec, s[34:35]
	v_ashrrev_i32_e32 v175, 31, v174
	v_mul_lo_u32 v217, s71, v174
	v_ashrrev_i32_e32 v173, 31, v172
	v_mul_lo_u32 v209, s71, v172
	v_ashrrev_i32_e32 v171, 31, v170
	v_mul_lo_u32 v208, s71, v170
	v_ashrrev_i32_e32 v207, 31, v205
	v_mul_lo_u32 v206, s71, v205
	v_add_u32_e32 v169, 0x90, v168
	v_add_u32_e32 v56, 0xa0, v168
	s_cbranch_vccnz .LBB0_291
; __device__ __forceinline__ u32x4 pack8(const f32x4& v0, const f32x4& v1) { u32x4 w; w.x = cvt_pk_bf16(v0[0], v0[1]); w.y = cvt_pk_bf16(v0[2], v0[3]); w.z = cvt_pk_bf16(v1[0], v1[1]); w.w = cvt_pk_bf16(v1[2], v1[3]); return w; }
;     __device__ __forceinline__ void operator()(const i32x4 (&acc)[2][2][4][2], const Unit& u, int wr, int wc, int fr, int fq) const {
;     ...
;         if (!do_rope) {
; #pragma unroll
;             for (int ai = 0; ai < 2; ++ai)
; #pragma unroll
;                 for (int m = 0; m < 4; ++m) { const int row = row0 + ai * HALF + m * 16; bf16_t* rowp = base + (size_t)row * rstride + cw; const float rsv = RS[row];
; #pragma unroll
;                     for (int bj = 0; bj < 2; ++bj) *(u32x4*)(rowp + bj * bjstride) = pack8(__builtin_convertvector(acc[ai][bj][m][0], f32x4) * (csv[bj][0] * rsv), __builtin_convertvector(acc[ai][bj][m][1], f32x4) * (csv[bj][1] * rsv)); }
	s_waitcnt vmcnt(7)
	v_pk_mul_f32 v[42:43], v[40:41], v[178:179] op_sel_hi:[1,0]
	v_pk_mul_f32 v[44:45], v[38:39], v[178:179] op_sel_hi:[1,0]
	v_pk_mul_f32 v[52:53], v[42:43], v[186:187]
	v_pk_mul_f32 v[42:43], v[44:45], v[184:185]
	v_pk_mul_f32 v[44:45], v[36:37], v[178:179] op_sel_hi:[1,0]
	v_pk_mul_f32 v[218:219], v[34:35], v[178:179] op_sel_hi:[1,0]
	v_pk_mul_f32 v[220:221], v[44:45], v[182:183]
	v_pk_mul_f32 v[44:45], v[218:219], v[180:181]
	v_cvt_pk_bf16_f32 v42, v42, v43
	v_cvt_pk_bf16_f32 v43, v52, v53
	v_pk_mul_f32 v[218:219], v[26:27], v[178:179] op_sel_hi:[1,0]
	v_cvt_pk_bf16_f32 v44, v44, v45
	v_cvt_pk_bf16_f32 v45, v220, v221
	global_store_dwordx4 v[176:177], v[42:45], off
	s_lshl_b32 s6, s86, 1
	v_readlane_b32 s28, v243, 51
	v_pk_mul_f32 v[42:43], v[32:33], v[178:179] op_sel_hi:[1,0]
	v_pk_mul_f32 v[44:45], v[30:31], v[178:179] op_sel_hi:[1,0]
	v_pk_mul_f32 v[52:53], v[42:43], v[144:145]
	v_pk_mul_f32 v[42:43], v[44:45], v[142:143]
	v_pk_mul_f32 v[44:45], v[28:29], v[178:179] op_sel_hi:[1,0]
	v_cvt_pk_bf16_f32 v42, v42, v43
	v_cvt_pk_bf16_f32 v43, v52, v53
	v_lshl_add_u64 v[52:53], v[176:177], 0, s[6:7]
	v_pk_mul_f32 v[220:221], v[44:45], v[140:141]
	v_pk_mul_f32 v[44:45], v[218:219], v[138:139]
	v_readlane_b32 s29, v243, 52
	v_cvt_pk_bf16_f32 v44, v44, v45
	v_cvt_pk_bf16_f32 v45, v220, v221
	global_store_dwordx4 v[52:53], v[42:45], off
	s_nop 1
	v_mul_lo_u32 v44, s70, v175
	v_mad_u64_u32 v[42:43], s[2:3], s70, v174, 0
	v_add3_u32 v43, v43, v44, v217
	v_lshl_add_u64 v[52:53], v[42:43], 1, v[164:165]
	v_lshl_add_u64 v[42:43], v[174:175], 2, s[28:29]
	s_waitcnt vmcnt(8)
	v_mov_b32_e32 v218, v244
	v_pk_mul_f32 v[42:43], v[38:39], v[218:219] op_sel_hi:[1,0]
	v_pk_mul_f32 v[44:45], v[40:41], v[218:219] op_sel_hi:[1,0]
	v_pk_mul_f32 v[42:43], v[42:43], v[134:135]
	v_pk_mul_f32 v[44:45], v[44:45], v[136:137]
	v_pk_mul_f32 v[220:221], v[34:35], v[218:219] op_sel_hi:[1,0]
	v_pk_mul_f32 v[222:223], v[36:37], v[218:219] op_sel_hi:[1,0]
	v_pk_mul_f32 v[220:221], v[220:221], v[130:131]
	v_pk_mul_f32 v[222:223], v[222:223], v[132:133]
	v_cvt_pk_bf16_f32 v42, v42, v43
	v_cvt_pk_bf16_f32 v43, v44, v45
	v_cvt_pk_bf16_f32 v44, v220, v221
	v_pk_mul_f32 v[220:221], v[26:27], v[218:219] op_sel_hi:[1,0]
	v_cvt_pk_bf16_f32 v45, v222, v223
	global_store_dwordx4 v[52:53], v[42:45], off
	v_pk_mul_f32 v[220:221], v[220:221], v[122:123]
	v_lshl_add_u64 v[52:53], v[52:53], 0, s[6:7]
	v_pk_mul_f32 v[42:43], v[30:31], v[218:219] op_sel_hi:[1,0]
	v_pk_mul_f32 v[44:45], v[32:33], v[218:219] op_sel_hi:[1,0]
	v_pk_mul_f32 v[42:43], v[42:43], v[124:125]
	v_pk_mul_f32 v[44:45], v[44:45], v[128:129]
	v_pk_mul_f32 v[218:219], v[28:29], v[218:219] op_sel_hi:[1,0]
	v_cvt_pk_bf16_f32 v42, v42, v43
	v_cvt_pk_bf16_f32 v43, v44, v45
	v_cvt_pk_bf16_f32 v44, v220, v221
	s_nop 0
	v_pk_mul_f32 v[218:219], v[218:219], v[126:127]
	s_nop 0
	v_cvt_pk_bf16_f32 v45, v218, v219
	global_store_dwordx4 v[52:53], v[42:45], off
	s_nop 1
	v_mul_lo_u32 v44, s70, v173
	v_mad_u64_u32 v[42:43], s[2:3], s70, v172, 0
	v_add3_u32 v43, v43, v44, v209
	v_lshl_add_u64 v[44:45], v[172:173], 2, s[28:29]
	v_lshl_add_u64 v[42:43], v[42:43], 1, v[164:165]
	s_waitcnt vmcnt(9)
	v_mov_b32_e32 v44, v245
	v_pk_mul_f32 v[218:219], v[40:41], v[44:45] op_sel_hi:[1,0]
	v_pk_mul_f32 v[52:53], v[38:39], v[44:45] op_sel_hi:[1,0]
	v_pk_mul_f32 v[220:221], v[218:219], v[120:121]
	v_pk_mul_f32 v[218:219], v[34:35], v[44:45] op_sel_hi:[1,0]
	v_pk_mul_f32 v[52:53], v[52:53], v[118:119]
	v_pk_mul_f32 v[222:223], v[36:37], v[44:45] op_sel_hi:[1,0]
	v_pk_mul_f32 v[224:225], v[218:219], v[114:115]
	v_cvt_pk_bf16_f32 v218, v52, v53
	v_cvt_pk_bf16_f32 v219, v220, v221
	v_pk_mul_f32 v[222:223], v[222:223], v[116:117]
	v_cvt_pk_bf16_f32 v220, v224, v225
	v_pk_mul_f32 v[52:53], v[30:31], v[44:45] op_sel_hi:[1,0]
	v_cvt_pk_bf16_f32 v221, v222, v223
	global_store_dwordx4 v[42:43], v[218:221], off
	v_lshl_add_u64 v[42:43], v[42:43], 0, s[6:7]
	v_pk_mul_f32 v[52:53], v[52:53], v[108:109]
	v_pk_mul_f32 v[218:219], v[32:33], v[44:45] op_sel_hi:[1,0]
	s_nop 0
	v_pk_mul_f32 v[220:221], v[218:219], v[112:113]
	v_pk_mul_f32 v[218:219], v[26:27], v[44:45] op_sel_hi:[1,0]
	v_pk_mul_f32 v[44:45], v[28:29], v[44:45] op_sel_hi:[1,0]
	v_pk_mul_f32 v[222:223], v[218:219], v[106:107]
	v_pk_mul_f32 v[44:45], v[44:45], v[110:111]
	v_cvt_pk_bf16_f32 v218, v52, v53
	v_cvt_pk_bf16_f32 v219, v220, v221
	v_cvt_pk_bf16_f32 v220, v222, v223
	s_nop 0
	v_cvt_pk_bf16_f32 v221, v44, v45
	global_store_dwordx4 v[42:43], v[218:221], off
	v_mul_lo_u32 v44, s70, v171
	v_mad_u64_u32 v[42:43], s[2:3], s70, v170, 0
	v_add3_u32 v43, v43, v44, v208
	v_lshl_add_u64 v[44:45], v[170:171], 2, s[28:29]
	v_lshl_add_u64 v[42:43], v[42:43], 1, v[164:165]
	s_waitcnt vmcnt(10)
	v_mov_b32_e32 v44, v246
	v_pk_mul_f32 v[218:219], v[40:41], v[44:45] op_sel_hi:[1,0]
	v_pk_mul_f32 v[52:53], v[38:39], v[44:45] op_sel_hi:[1,0]
	v_pk_mul_f32 v[220:221], v[218:219], v[104:105]
	v_pk_mul_f32 v[218:219], v[34:35], v[44:45] op_sel_hi:[1,0]
	v_pk_mul_f32 v[52:53], v[52:53], v[102:103]
	v_pk_mul_f32 v[222:223], v[36:37], v[44:45] op_sel_hi:[1,0]
	v_pk_mul_f32 v[224:225], v[218:219], v[98:99]
	v_cvt_pk_bf16_f32 v218, v52, v53
	v_cvt_pk_bf16_f32 v219, v220, v221
	v_pk_mul_f32 v[222:223], v[222:223], v[100:101]
	v_cvt_pk_bf16_f32 v220, v224, v225
	v_pk_mul_f32 v[52:53], v[30:31], v[44:45] op_sel_hi:[1,0]
	v_cvt_pk_bf16_f32 v221, v222, v223
	global_store_dwordx4 v[42:43], v[218:221], off
	v_lshl_add_u64 v[42:43], v[42:43], 0, s[6:7]
	v_pk_mul_f32 v[52:53], v[52:53], v[92:93]
	v_pk_mul_f32 v[218:219], v[32:33], v[44:45] op_sel_hi:[1,0]
	s_nop 0
	v_pk_mul_f32 v[220:221], v[218:219], v[96:97]
	v_pk_mul_f32 v[218:219], v[26:27], v[44:45] op_sel_hi:[1,0]
	v_pk_mul_f32 v[44:45], v[28:29], v[44:45] op_sel_hi:[1,0]
	v_pk_mul_f32 v[222:223], v[218:219], v[90:91]
	v_pk_mul_f32 v[44:45], v[44:45], v[94:95]
	v_cvt_pk_bf16_f32 v218, v52, v53
	v_cvt_pk_bf16_f32 v219, v220, v221
	v_cvt_pk_bf16_f32 v220, v222, v223
	s_nop 0
	v_cvt_pk_bf16_f32 v221, v44, v45
	global_store_dwordx4 v[42:43], v[218:221], off
	v_mul_lo_u32 v44, s70, v207
	v_mad_u64_u32 v[42:43], s[2:3], s70, v205, 0
	v_add3_u32 v43, v43, v44, v206
	v_lshl_add_u64 v[52:53], v[42:43], 1, v[164:165]
	s_waitcnt vmcnt(11)
; __device__ __forceinline__ u32x4 pack8(const f32x4& v0, const f32x4& v1) { u32x4 w; w.x = cvt_pk_bf16(v0[0], v0[1]); w.y = cvt_pk_bf16(v0[2], v0[3]); w.z = cvt_pk_bf16(v1[0], v1[1]); w.w = cvt_pk_bf16(v1[2], v1[3]); return w; }
;     __device__ __forceinline__ void operator()(const i32x4 (&acc)[2][2][4][2], const Unit& u, int wr, int wc, int fr, int fq) const {
;     ...
;         if (!do_rope) {
; #pragma unroll
;             for (int ai = 0; ai < 2; ++ai)
; #pragma unroll
;                 for (int m = 0; m < 4; ++m) { const int row = row0 + ai * HALF + m * 16; bf16_t* rowp = base + (size_t)row * rstride + cw; const float rsv = RS[row];
; #pragma unroll
;                     for (int bj = 0; bj < 2; ++bj) *(u32x4*)(rowp + bj * bjstride) = pack8(__builtin_convertvector(acc[ai][bj][m][0], f32x4) * (csv[bj][0] * rsv), __builtin_convertvector(acc[ai][bj][m][1], f32x4) * (csv[bj][1] * rsv)); }
	v_mov_b32_e32 v218, v247
	v_pk_mul_f32 v[42:43], v[40:41], v[218:219] op_sel_hi:[1,0]
	v_pk_mul_f32 v[44:45], v[38:39], v[218:219] op_sel_hi:[1,0]
	v_pk_mul_f32 v[220:221], v[42:43], v[88:89]
	v_pk_mul_f32 v[42:43], v[44:45], v[84:85]
	v_pk_mul_f32 v[44:45], v[36:37], v[218:219] op_sel_hi:[1,0]
	v_pk_mul_f32 v[222:223], v[34:35], v[218:219] op_sel_hi:[1,0]
	v_pk_mul_f32 v[224:225], v[44:45], v[86:87]
	v_pk_mul_f32 v[44:45], v[222:223], v[82:83]
	v_cvt_pk_bf16_f32 v42, v42, v43
	v_cvt_pk_bf16_f32 v43, v220, v221
	s_nop 0
	v_cvt_pk_bf16_f32 v44, v44, v45
	v_cvt_pk_bf16_f32 v45, v224, v225
	global_store_dwordx4 v[52:53], v[42:45], off
	v_lshl_add_u64 v[52:53], v[52:53], 0, s[6:7]
	s_nop 0
	v_pk_mul_f32 v[42:43], v[32:33], v[218:219] op_sel_hi:[1,0]
	v_pk_mul_f32 v[44:45], v[30:31], v[218:219] op_sel_hi:[1,0]
	v_pk_mul_f32 v[220:221], v[42:43], v[80:81]
	v_pk_mul_f32 v[42:43], v[44:45], v[76:77]
	v_pk_mul_f32 v[44:45], v[28:29], v[218:219] op_sel_hi:[1,0]
	v_pk_mul_f32 v[218:219], v[26:27], v[218:219] op_sel_hi:[1,0]
	v_pk_mul_f32 v[222:223], v[44:45], v[78:79]
	v_pk_mul_f32 v[44:45], v[218:219], v[74:75]
	v_cvt_pk_bf16_f32 v42, v42, v43
	v_cvt_pk_bf16_f32 v43, v220, v221
	s_nop 0
	v_cvt_pk_bf16_f32 v44, v44, v45
	v_cvt_pk_bf16_f32 v45, v222, v223
	global_store_dwordx4 v[52:53], v[42:45], off
	s_waitcnt vmcnt(12)
	v_mov_b32_e32 v218, v248
	v_pk_mul_f32 v[222:223], v[34:35], v[218:219] op_sel_hi:[1,0]
	v_ashrrev_i32_e32 v42, 31, v169
	v_mul_lo_u32 v44, s70, v42
	v_mul_lo_u32 v45, s71, v169
	v_mad_u64_u32 v[42:43], s[2:3], s70, v169, 0
	v_add3_u32 v43, v43, v44, v45
	v_lshl_add_u64 v[52:53], v[42:43], 1, v[164:165]
	v_pk_mul_f32 v[42:43], v[40:41], v[218:219] op_sel_hi:[1,0]
	v_pk_mul_f32 v[44:45], v[38:39], v[218:219] op_sel_hi:[1,0]
	v_pk_mul_f32 v[220:221], v[42:43], v[72:73]
	v_pk_mul_f32 v[42:43], v[44:45], v[70:71]
	v_pk_mul_f32 v[44:45], v[36:37], v[218:219] op_sel_hi:[1,0]
	v_cvt_pk_bf16_f32 v42, v42, v43
	v_cvt_pk_bf16_f32 v43, v220, v221
	s_nop 0
	v_pk_mul_f32 v[224:225], v[44:45], v[68:69]
	v_pk_mul_f32 v[44:45], v[222:223], v[66:67]
	s_nop 0
	v_cvt_pk_bf16_f32 v44, v44, v45
	v_cvt_pk_bf16_f32 v45, v224, v225
	global_store_dwordx4 v[52:53], v[42:45], off
	v_lshl_add_u64 v[52:53], v[52:53], 0, s[6:7]
	s_nop 0
	v_pk_mul_f32 v[42:43], v[32:33], v[218:219] op_sel_hi:[1,0]
	v_pk_mul_f32 v[44:45], v[30:31], v[218:219] op_sel_hi:[1,0]
	v_pk_mul_f32 v[220:221], v[42:43], v[64:65]
	v_pk_mul_f32 v[42:43], v[44:45], v[60:61]
	v_pk_mul_f32 v[44:45], v[28:29], v[218:219] op_sel_hi:[1,0]
	v_pk_mul_f32 v[218:219], v[26:27], v[218:219] op_sel_hi:[1,0]
	v_pk_mul_f32 v[222:223], v[44:45], v[62:63]
	v_pk_mul_f32 v[44:45], v[218:219], v[58:59]
	v_cvt_pk_bf16_f32 v42, v42, v43
	v_cvt_pk_bf16_f32 v43, v220, v221
	s_nop 0
	v_cvt_pk_bf16_f32 v44, v44, v45
	v_cvt_pk_bf16_f32 v45, v222, v223
	global_store_dwordx4 v[52:53], v[42:45], off
	s_waitcnt vmcnt(13)
	v_mov_b32_e32 v218, v249
	v_pk_mul_f32 v[222:223], v[34:35], v[218:219] op_sel_hi:[1,0]
	v_ashrrev_i32_e32 v42, 31, v56
	v_mul_lo_u32 v44, s70, v42
	v_mul_lo_u32 v45, s71, v56
	v_mad_u64_u32 v[42:43], s[2:3], s70, v56, 0
	v_add3_u32 v43, v43, v44, v45
	v_lshl_add_u64 v[52:53], v[42:43], 1, v[164:165]
	v_pk_mul_f32 v[42:43], v[40:41], v[218:219] op_sel_hi:[1,0]
	v_pk_mul_f32 v[44:45], v[38:39], v[218:219] op_sel_hi:[1,0]
	v_pk_mul_f32 v[220:221], v[42:43], v[54:55]
	v_pk_mul_f32 v[42:43], v[44:45], v[48:49]
	v_pk_mul_f32 v[44:45], v[36:37], v[218:219] op_sel_hi:[1,0]
	v_cvt_pk_bf16_f32 v42, v42, v43
	v_cvt_pk_bf16_f32 v43, v220, v221
	v_pk_mul_f32 v[220:221], v[32:33], v[218:219] op_sel_hi:[1,0]
	v_pk_mul_f32 v[224:225], v[44:45], v[50:51]
	v_pk_mul_f32 v[44:45], v[222:223], v[46:47]
	v_pk_mul_f32 v[222:223], v[30:31], v[218:219] op_sel_hi:[1,0]
	v_cvt_pk_bf16_f32 v44, v44, v45
	v_cvt_pk_bf16_f32 v45, v224, v225
	global_store_dwordx4 v[52:53], v[42:45], off
	v_pk_mul_f32 v[224:225], v[28:29], v[218:219] op_sel_hi:[1,0]
	v_pk_mul_f32 v[218:219], v[26:27], v[218:219] op_sel_hi:[1,0]
	v_cvt_f32_i32_e32 v43, v23
	v_cvt_f32_i32_e32 v42, v22
	v_cvt_f32_i32_e32 v45, v25
	v_cvt_f32_i32_e32 v44, v24
	v_lshl_add_u64 v[52:53], v[52:53], 0, s[6:7]
	v_pk_mul_f32 v[42:43], v[222:223], v[42:43]
	v_cvt_f32_i32_e32 v223, v21
	v_pk_mul_f32 v[44:45], v[220:221], v[44:45]
	v_cvt_f32_i32_e32 v221, v19
	v_cvt_f32_i32_e32 v220, v18
	v_cvt_f32_i32_e32 v222, v20
	v_cvt_pk_bf16_f32 v42, v42, v43
	v_cvt_pk_bf16_f32 v43, v44, v45
	v_pk_mul_f32 v[218:219], v[218:219], v[220:221]
	v_pk_mul_f32 v[222:223], v[224:225], v[222:223]
	v_cvt_pk_bf16_f32 v44, v218, v219
	s_nop 0
	v_cvt_pk_bf16_f32 v45, v222, v223
	global_store_dwordx4 v[52:53], v[42:45], off
	s_waitcnt vmcnt(14)
	v_mov_b32_e32 v220, v250
	v_pk_mul_f32 v[222:223], v[40:41], v[220:221] op_sel_hi:[1,0]
	v_add_u32_e32 v42, 0xb0, v168
	v_ashrrev_i32_e32 v43, 31, v42
	v_mul_lo_u32 v43, s70, v43
	v_mul_lo_u32 v44, s71, v42
	v_mad_u64_u32 v[52:53], s[2:3], s70, v42, 0
	v_add3_u32 v53, v53, v43, v44
	v_cvt_f32_i32_e32 v43, v15
	v_cvt_f32_i32_e32 v42, v14
	v_cvt_f32_i32_e32 v45, v17
	v_cvt_f32_i32_e32 v44, v16
	v_pk_mul_f32 v[224:225], v[38:39], v[220:221] op_sel_hi:[1,0]
	v_pk_mul_f32 v[226:227], v[36:37], v[220:221] op_sel_hi:[1,0]
	v_pk_mul_f32 v[42:43], v[224:225], v[42:43]
	v_pk_mul_f32 v[44:45], v[222:223], v[44:45]
	v_cvt_f32_i32_e32 v223, v11
	v_cvt_f32_i32_e32 v222, v10
	v_cvt_f32_i32_e32 v225, v13
	v_cvt_f32_i32_e32 v224, v12
	v_pk_mul_f32 v[228:229], v[34:35], v[220:221] op_sel_hi:[1,0]
	v_lshl_add_u64 v[218:219], v[52:53], 1, v[164:165]
	v_pk_mul_f32 v[222:223], v[228:229], v[222:223]
	v_pk_mul_f32 v[224:225], v[226:227], v[224:225]
	v_cvt_pk_bf16_f32 v42, v42, v43
	v_cvt_pk_bf16_f32 v43, v44, v45
	v_cvt_pk_bf16_f32 v44, v222, v223
	v_pk_mul_f32 v[222:223], v[30:31], v[220:221] op_sel_hi:[1,0]
	v_cvt_pk_bf16_f32 v45, v224, v225
	global_store_dwordx4 v[218:219], v[42:45], off
	v_pk_mul_f32 v[218:219], v[32:33], v[220:221] op_sel_hi:[1,0]
	v_pk_mul_f32 v[224:225], v[28:29], v[220:221] op_sel_hi:[1,0]
	v_cvt_f32_i32_e32 v43, v7
	v_cvt_f32_i32_e32 v42, v6
	v_cvt_f32_i32_e32 v45, v9
	v_cvt_f32_i32_e32 v44, v8
	v_pk_mul_f32 v[220:221], v[26:27], v[220:221] op_sel_hi:[1,0]
	v_pk_mul_f32 v[42:43], v[222:223], v[42:43]
	v_cvt_f32_i32_e32 v223, v5
	v_pk_mul_f32 v[44:45], v[218:219], v[44:45]
	v_cvt_f32_i32_e32 v219, v3
	v_cvt_f32_i32_e32 v218, v2
	v_cvt_f32_i32_e32 v222, v4
	s_mov_b64 s[2:3], 0
	v_cvt_pk_bf16_f32 v42, v42, v43
	v_pk_mul_f32 v[218:219], v[220:221], v[218:219]
	v_pk_mul_f32 v[222:223], v[224:225], v[222:223]
	v_cvt_pk_bf16_f32 v43, v44, v45
	v_cvt_pk_bf16_f32 v44, v218, v219
	s_nop 0
	v_cvt_pk_bf16_f32 v45, v222, v223

; __global__ void __launch_bounds__(NWAVES * 64, 2) fwd_kernel(Args args) {
	.amdhsa_kernel _Z10fwd_kernel4Args
		.amdhsa_group_segment_fixed_size 0
		.amdhsa_private_segment_fixed_size 0
		.amdhsa_kernarg_size 464
		.amdhsa_user_sgpr_count 2
		.amdhsa_user_sgpr_dispatch_ptr 0
		.amdhsa_user_sgpr_queue_ptr 0
		.amdhsa_user_sgpr_kernarg_segment_ptr 1
		.amdhsa_user_sgpr_dispatch_id 0
		.amdhsa_user_sgpr_kernarg_preload_length 0
		.amdhsa_user_sgpr_kernarg_preload_offset 0
		.amdhsa_user_sgpr_private_segment_size 0
		.amdhsa_uses_dynamic_stack 0
		.amdhsa_enable_private_segment 0
		.amdhsa_system_sgpr_workgroup_id_x 1
		.amdhsa_system_sgpr_workgroup_id_y 0
		.amdhsa_system_sgpr_workgroup_id_z 0
		.amdhsa_system_sgpr_workgroup_info 0
		.amdhsa_system_vgpr_workitem_id 0
		.amdhsa_next_free_vgpr 256
		.amdhsa_next_free_sgpr 98
		.amdhsa_accum_offset 256
		.amdhsa_reserve_vcc 1
		.amdhsa_float_round_mode_32 0
		.amdhsa_float_round_mode_16_64 0
		.amdhsa_float_denorm_mode_32 3
		.amdhsa_float_denorm_mode_16_64 3
		.amdhsa_dx10_clamp 1
		.amdhsa_ieee_mode 1
		.amdhsa_fp16_overflow 0
		.amdhsa_tg_split 0
		.amdhsa_exception_fp_ieee_invalid_op 0
		.amdhsa_exception_fp_denorm_src 0
		.amdhsa_exception_fp_ieee_div_zero 0
		.amdhsa_exception_fp_ieee_overflow 0
		.amdhsa_exception_fp_ieee_underflow 0
		.amdhsa_exception_fp_ieee_inexact 0
		.amdhsa_exception_int_div_zero 0
	.end_amdhsa_kernel

; __global__ void __launch_bounds__(NWAVES * 64, 2) fwd_kernel(Args args) {
amdhsa.kernels:
  - .agpr_count:     0
    .args:
      - .offset:         0
        .size:           208
        .value_kind:     by_value
      - .offset:         208
        .size:           4
        .value_kind:     hidden_block_count_x
      - .offset:         212
        .size:           4
        .value_kind:     hidden_block_count_y
      - .offset:         216
        .size:           4
        .value_kind:     hidden_block_count_z
      - .offset:         220
        .size:           2
        .value_kind:     hidden_group_size_x
      - .offset:         222
        .size:           2
        .value_kind:     hidden_group_size_y
      - .offset:         224
        .size:           2
        .value_kind:     hidden_group_size_z
      - .offset:         226
        .size:           2
        .value_kind:     hidden_remainder_x
      - .offset:         228
        .size:           2
        .value_kind:     hidden_remainder_y
      - .offset:         230
        .size:           2
        .value_kind:     hidden_remainder_z
      - .offset:         248
        .size:           8
        .value_kind:     hidden_global_offset_x
      - .offset:         256
        .size:           8
        .value_kind:     hidden_global_offset_y
      - .offset:         264
        .size:           8
        .value_kind:     hidden_global_offset_z
      - .offset:         272
        .size:           2
        .value_kind:     hidden_grid_dims
      - .offset:         328
        .size:           4
        .value_kind:     hidden_dynamic_lds_size
    .group_segment_fixed_size: 0
    .kernarg_segment_align: 8
    .kernarg_segment_size: 464
    .language:       OpenCL C
    .language_version:
      - 2
      - 0
    .max_flat_workgroup_size: 512
    .name:           _Z10fwd_kernel4Args
    .private_segment_fixed_size: 0
    .sgpr_count:     104
    .sgpr_spill_count: 115
    .symbol:         _Z10fwd_kernel4Args.kd
    .uniform_work_group_size: 1
    .uses_dynamic_stack: false
    .vgpr_count:     256
    .vgpr_spill_count: 0
    .wavefront_size: 64
